# v81 stack plus PH9 loop LDS read addresses folded into ds_read offsets and the never-taken rsqrt denormal guards removed in all GEMM epilogues
# baseline (speedup 1.0000x reference)
; #define SBAR() __builtin_amdgcn_sched_barrier(0)
; __device__ __forceinline__ float fast_sigmoid(float x) { return __builtin_amdgcn_rcpf(1.0f + __builtin_amdgcn_exp2f(-1.4426950408889634f * x)); }
; __device__ __forceinline__ u32x4 pack8(const f32x4 a, const f32x4 b) { u32x4 w; w.x = cvt_pk_bf16(a[0], a[1]); w.y = cvt_pk_bf16(a[2], a[3]); w.z = cvt_pk_bf16(b[0], b[1]); w.w = cvt_pk_bf16(b[2], b[3]); return w; }
;     __device__ __forceinline__ void operator()(f32x4 (&acc)[2][2][4][2], const Unit& u, int wr, int wc, int fr, int fq) const {
;     ...
;             float rsv[8];
; #pragma unroll
;             for (int i = 0; i < 8; ++i) rsv[i] = P.ssq_h1_()[ROWOF(i >> 2, i & 3)];
;             SBAR();
; #pragma unroll
;             for (int ai = 0; ai < 2; ++ai)
; #pragma unroll
;                 for (int m = 0; m < 4; ++m) { const int row = ROWOF(ai, m); const float rs = rsqrtf(rsv[ai * 4 + m] * (1.0f / 2048.0f) + EPS);
;                     f32x4 g0 = acc[ai][0][m][0] * rs, g1 = acc[ai][0][m][1] * rs; const f32x4 u0 = acc[ai][1][m][0] * rs, u1 = acc[ai][1][m][1] * rs;
; #pragma unroll
;                     for (int j = 0; j < 4; ++j) { g0[j] = g0[j] * fast_sigmoid(g0[j]) * u0[j]; g1[j] = g1[j] * fast_sigmoid(g1[j]) * u1[j]; }
;                     *(u32x4*)(P.f_() + (size_t)row * DFF + u.pn * 128 + c8) = pack8(g0, g1); }
.LBB0_1002:
	v_lshl_add_u32 v146, s22, 8, v150
	v_ashrrev_i32_e32 v147, 31, v146
	v_lshl_add_u64 v[156:157], v[146:147], 2, s[10:11]
	global_load_dword v158, v[156:157], off
	global_load_dword v159, v[156:157], off offset:64
	global_load_dword v164, v[156:157], off offset:128
	global_load_dword v165, v[156:157], off offset:192
	global_load_dword v166, v[156:157], off offset:512
	global_load_dword v149, v[156:157], off offset:576
	global_load_dword v148, v[156:157], off offset:640
	global_load_dword v147, v[156:157], off offset:704
	v_add_u32_e32 v156, 0x80, v146
	s_waitcnt vmcnt(0)
	s_lshl_b32 s22, s23, 7
	s_ashr_i32 s23, s22, 31
	s_lshl_b64 s[22:23], s[22:23], 1
	s_add_u32 s98, s12, s22
	s_addc_u32 s99, s13, s23
	s_mov_b32 s36, 0xbfb8aa3b
	s_mov_b32 s37, 0xbfb8aa3b
	s_mov_b32 s38, 1.0
	s_mov_b32 s39, 1.0
	v_fmamk_f32 v228, v158, 0x3a000000, v155
	s_nop 1
	v_mad_u32_u24 v157, v146, s52, v134
	v_rsq_f32_e32 v228, v228
	s_nop 0
	s_nop 0
	v_pk_mul_f32 v[126:127], v[126:127], v[228:229] op_sel_hi:[1,0]
	v_pk_mul_f32 v[128:129], v[128:129], v[228:229] op_sel_hi:[1,0]
	v_pk_mul_f32 v[122:123], v[122:123], v[228:229] op_sel_hi:[1,0]
	v_pk_mul_f32 v[124:125], v[124:125], v[228:229] op_sel_hi:[1,0]
	v_pk_mul_f32 v[118:119], v[118:119], v[228:229] op_sel_hi:[1,0]
	v_pk_mul_f32 v[120:121], v[120:121], v[228:229] op_sel_hi:[1,0]
	v_pk_mul_f32 v[114:115], v[114:115], v[228:229] op_sel_hi:[1,0]
	v_pk_mul_f32 v[116:117], v[116:117], v[228:229] op_sel_hi:[1,0]
	v_pk_mul_f32 v[220:221], v[126:127], s[36:37]
	v_pk_mul_f32 v[222:223], v[128:129], s[36:37]
	v_pk_mul_f32 v[224:225], v[122:123], s[36:37]
	v_pk_mul_f32 v[226:227], v[124:125], s[36:37]
	v_exp_f32_e32 v220, v220
	v_exp_f32_e32 v221, v221
	v_exp_f32_e32 v222, v222
	v_exp_f32_e32 v223, v223
	v_exp_f32_e32 v224, v224
	v_exp_f32_e32 v225, v225
	v_exp_f32_e32 v226, v226
	v_exp_f32_e32 v227, v227
	v_pk_add_f32 v[220:221], v[220:221], s[38:39]
	v_pk_add_f32 v[222:223], v[222:223], s[38:39]
	v_pk_add_f32 v[224:225], v[224:225], s[38:39]
	v_pk_add_f32 v[226:227], v[226:227], s[38:39]
	v_rcp_f32_e32 v220, v220
	v_rcp_f32_e32 v221, v221
	v_rcp_f32_e32 v222, v222
	v_rcp_f32_e32 v223, v223
	v_rcp_f32_e32 v224, v224
	v_rcp_f32_e32 v225, v225
	v_rcp_f32_e32 v226, v226
	v_rcp_f32_e32 v227, v227
	v_pk_mul_f32 v[126:127], v[126:127], v[220:221]
	v_pk_mul_f32 v[128:129], v[128:129], v[222:223]
	v_pk_mul_f32 v[122:123], v[122:123], v[224:225]
	v_pk_mul_f32 v[124:125], v[124:125], v[226:227]
	v_pk_mul_f32 v[118:119], v[118:119], v[126:127]
	v_pk_mul_f32 v[120:121], v[120:121], v[128:129]
	v_pk_mul_f32 v[114:115], v[114:115], v[122:123]
	v_pk_mul_f32 v[116:117], v[116:117], v[124:125]
	v_cvt_pk_bf16_f32 v126, v118, v119
	v_cvt_pk_bf16_f32 v127, v120, v121
	v_cvt_pk_bf16_f32 v128, v114, v115
	v_cvt_pk_bf16_f32 v129, v116, v117
	global_store_dwordx4 v157, v[126:129], s[98:99] nt
	v_fmamk_f32 v228, v159, 0x3a000000, v155
	v_or_b32_e32 v156, 0x10, v146
	s_nop 0
	v_mad_u32_u24 v160, v156, s52, v134
	v_rsq_f32_e32 v228, v228
	s_nop 0
	s_nop 0
	v_pk_mul_f32 v[110:111], v[110:111], v[228:229] op_sel_hi:[1,0]
	v_pk_mul_f32 v[112:113], v[112:113], v[228:229] op_sel_hi:[1,0]
	v_pk_mul_f32 v[106:107], v[106:107], v[228:229] op_sel_hi:[1,0]
	v_pk_mul_f32 v[108:109], v[108:109], v[228:229] op_sel_hi:[1,0]
	v_pk_mul_f32 v[102:103], v[102:103], v[228:229] op_sel_hi:[1,0]
	v_pk_mul_f32 v[104:105], v[104:105], v[228:229] op_sel_hi:[1,0]
	v_pk_mul_f32 v[98:99], v[98:99], v[228:229] op_sel_hi:[1,0]
	v_pk_mul_f32 v[100:101], v[100:101], v[228:229] op_sel_hi:[1,0]
	v_pk_mul_f32 v[220:221], v[110:111], s[36:37]
	v_pk_mul_f32 v[222:223], v[112:113], s[36:37]
	v_pk_mul_f32 v[224:225], v[106:107], s[36:37]
	v_pk_mul_f32 v[226:227], v[108:109], s[36:37]
	v_exp_f32_e32 v220, v220
	v_exp_f32_e32 v221, v221
	v_exp_f32_e32 v222, v222
	v_exp_f32_e32 v223, v223
	v_exp_f32_e32 v224, v224
	v_exp_f32_e32 v225, v225
	v_exp_f32_e32 v226, v226
	v_exp_f32_e32 v227, v227
	v_pk_add_f32 v[220:221], v[220:221], s[38:39]
	v_pk_add_f32 v[222:223], v[222:223], s[38:39]
	v_pk_add_f32 v[224:225], v[224:225], s[38:39]
	v_pk_add_f32 v[226:227], v[226:227], s[38:39]
	v_rcp_f32_e32 v220, v220
	v_rcp_f32_e32 v221, v221
	v_rcp_f32_e32 v222, v222
	v_rcp_f32_e32 v223, v223
	v_rcp_f32_e32 v224, v224
	v_rcp_f32_e32 v225, v225
	v_rcp_f32_e32 v226, v226
	v_rcp_f32_e32 v227, v227
	v_pk_mul_f32 v[110:111], v[110:111], v[220:221]
	v_pk_mul_f32 v[112:113], v[112:113], v[222:223]
	v_pk_mul_f32 v[106:107], v[106:107], v[224:225]
	v_pk_mul_f32 v[108:109], v[108:109], v[226:227]
	v_pk_mul_f32 v[102:103], v[102:103], v[110:111]
	v_pk_mul_f32 v[104:105], v[104:105], v[112:113]
	v_pk_mul_f32 v[98:99], v[98:99], v[106:107]
	v_pk_mul_f32 v[100:101], v[100:101], v[108:109]
	v_cvt_pk_bf16_f32 v110, v102, v103
	v_cvt_pk_bf16_f32 v111, v104, v105
	v_cvt_pk_bf16_f32 v112, v98, v99
	v_cvt_pk_bf16_f32 v113, v100, v101
	global_store_dwordx4 v160, v[110:113], s[98:99] nt
	v_fmamk_f32 v228, v164, 0x3a000000, v155
	v_or_b32_e32 v156, 0x20, v146
	s_nop 0
	v_mad_u32_u24 v157, v156, s52, v134
	v_rsq_f32_e32 v228, v228
	s_nop 0
	s_nop 0
	v_pk_mul_f32 v[94:95], v[94:95], v[228:229] op_sel_hi:[1,0]
	v_pk_mul_f32 v[96:97], v[96:97], v[228:229] op_sel_hi:[1,0]
	v_pk_mul_f32 v[90:91], v[90:91], v[228:229] op_sel_hi:[1,0]
	v_pk_mul_f32 v[92:93], v[92:93], v[228:229] op_sel_hi:[1,0]
	v_pk_mul_f32 v[86:87], v[86:87], v[228:229] op_sel_hi:[1,0]
	v_pk_mul_f32 v[88:89], v[88:89], v[228:229] op_sel_hi:[1,0]
	v_pk_mul_f32 v[82:83], v[82:83], v[228:229] op_sel_hi:[1,0]
	v_pk_mul_f32 v[84:85], v[84:85], v[228:229] op_sel_hi:[1,0]
	v_pk_mul_f32 v[220:221], v[94:95], s[36:37]
	v_pk_mul_f32 v[222:223], v[96:97], s[36:37]
; __device__ __forceinline__ float fast_sigmoid(float x) { return __builtin_amdgcn_rcpf(1.0f + __builtin_amdgcn_exp2f(-1.4426950408889634f * x)); }
; __device__ __forceinline__ u32x4 pack8(const f32x4 a, const f32x4 b) { u32x4 w; w.x = cvt_pk_bf16(a[0], a[1]); w.y = cvt_pk_bf16(a[2], a[3]); w.z = cvt_pk_bf16(b[0], b[1]); w.w = cvt_pk_bf16(b[2], b[3]); return w; }
;     __device__ __forceinline__ void operator()(f32x4 (&acc)[2][2][4][2], const Unit& u, int wr, int wc, int fr, int fq) const {
;     ...
;                 for (int m = 0; m < 4; ++m) { const int row = ROWOF(ai, m); const float rs = rsqrtf(rsv[ai * 4 + m] * (1.0f / 2048.0f) + EPS);
;                     f32x4 g0 = acc[ai][0][m][0] * rs, g1 = acc[ai][0][m][1] * rs; const f32x4 u0 = acc[ai][1][m][0] * rs, u1 = acc[ai][1][m][1] * rs;
; #pragma unroll
;                     for (int j = 0; j < 4; ++j) { g0[j] = g0[j] * fast_sigmoid(g0[j]) * u0[j]; g1[j] = g1[j] * fast_sigmoid(g1[j]) * u1[j]; }
;                     *(u32x4*)(P.f_() + (size_t)row * DFF + u.pn * 128 + c8) = pack8(g0, g1); }
	v_pk_mul_f32 v[224:225], v[90:91], s[36:37]
	v_pk_mul_f32 v[226:227], v[92:93], s[36:37]
	v_exp_f32_e32 v220, v220
	v_exp_f32_e32 v221, v221
	v_exp_f32_e32 v222, v222
	v_exp_f32_e32 v223, v223
	v_exp_f32_e32 v224, v224
	v_exp_f32_e32 v225, v225
	v_exp_f32_e32 v226, v226
	v_exp_f32_e32 v227, v227
	v_pk_add_f32 v[220:221], v[220:221], s[38:39]
	v_pk_add_f32 v[222:223], v[222:223], s[38:39]
	v_pk_add_f32 v[224:225], v[224:225], s[38:39]
	v_pk_add_f32 v[226:227], v[226:227], s[38:39]
	v_rcp_f32_e32 v220, v220
	v_rcp_f32_e32 v221, v221
	v_rcp_f32_e32 v222, v222
	v_rcp_f32_e32 v223, v223
	v_rcp_f32_e32 v224, v224
	v_rcp_f32_e32 v225, v225
	v_rcp_f32_e32 v226, v226
	v_rcp_f32_e32 v227, v227
	v_pk_mul_f32 v[94:95], v[94:95], v[220:221]
	v_pk_mul_f32 v[96:97], v[96:97], v[222:223]
	v_pk_mul_f32 v[90:91], v[90:91], v[224:225]
	v_pk_mul_f32 v[92:93], v[92:93], v[226:227]
	v_pk_mul_f32 v[86:87], v[86:87], v[94:95]
	v_pk_mul_f32 v[88:89], v[88:89], v[96:97]
	v_pk_mul_f32 v[82:83], v[82:83], v[90:91]
	v_pk_mul_f32 v[84:85], v[84:85], v[92:93]
	v_cvt_pk_bf16_f32 v94, v86, v87
	v_cvt_pk_bf16_f32 v95, v88, v89
	v_cvt_pk_bf16_f32 v96, v82, v83
	v_cvt_pk_bf16_f32 v97, v84, v85
	global_store_dwordx4 v157, v[94:97], s[98:99] nt
	v_fmamk_f32 v228, v165, 0x3a000000, v155
	v_or_b32_e32 v156, 0x30, v146
	s_nop 0
	v_mad_u32_u24 v160, v156, s52, v134
	v_rsq_f32_e32 v228, v228
	s_nop 0
	s_nop 0
	v_pk_mul_f32 v[78:79], v[78:79], v[228:229] op_sel_hi:[1,0]
	v_pk_mul_f32 v[80:81], v[80:81], v[228:229] op_sel_hi:[1,0]
	v_pk_mul_f32 v[74:75], v[74:75], v[228:229] op_sel_hi:[1,0]
	v_pk_mul_f32 v[76:77], v[76:77], v[228:229] op_sel_hi:[1,0]
	v_pk_mul_f32 v[70:71], v[70:71], v[228:229] op_sel_hi:[1,0]
	v_pk_mul_f32 v[72:73], v[72:73], v[228:229] op_sel_hi:[1,0]
	v_pk_mul_f32 v[66:67], v[66:67], v[228:229] op_sel_hi:[1,0]
	v_pk_mul_f32 v[68:69], v[68:69], v[228:229] op_sel_hi:[1,0]
	v_pk_mul_f32 v[220:221], v[78:79], s[36:37]
	v_pk_mul_f32 v[222:223], v[80:81], s[36:37]
	v_pk_mul_f32 v[224:225], v[74:75], s[36:37]
	v_pk_mul_f32 v[226:227], v[76:77], s[36:37]
	v_exp_f32_e32 v220, v220
	v_exp_f32_e32 v221, v221
	v_exp_f32_e32 v222, v222
	v_exp_f32_e32 v223, v223
	v_exp_f32_e32 v224, v224
	v_exp_f32_e32 v225, v225
	v_exp_f32_e32 v226, v226
	v_exp_f32_e32 v227, v227
	v_pk_add_f32 v[220:221], v[220:221], s[38:39]
	v_pk_add_f32 v[222:223], v[222:223], s[38:39]
	v_pk_add_f32 v[224:225], v[224:225], s[38:39]
	v_pk_add_f32 v[226:227], v[226:227], s[38:39]
	v_rcp_f32_e32 v220, v220
	v_rcp_f32_e32 v221, v221
	v_rcp_f32_e32 v222, v222
	v_rcp_f32_e32 v223, v223
	v_rcp_f32_e32 v224, v224
	v_rcp_f32_e32 v225, v225
	v_rcp_f32_e32 v226, v226
	v_rcp_f32_e32 v227, v227
	v_pk_mul_f32 v[78:79], v[78:79], v[220:221]
	v_pk_mul_f32 v[80:81], v[80:81], v[222:223]
	v_pk_mul_f32 v[74:75], v[74:75], v[224:225]
	v_pk_mul_f32 v[76:77], v[76:77], v[226:227]
	v_pk_mul_f32 v[70:71], v[70:71], v[78:79]
	v_pk_mul_f32 v[72:73], v[72:73], v[80:81]
	v_pk_mul_f32 v[66:67], v[66:67], v[74:75]
	v_pk_mul_f32 v[68:69], v[68:69], v[76:77]
	v_cvt_pk_bf16_f32 v78, v70, v71
	v_cvt_pk_bf16_f32 v79, v72, v73
	v_cvt_pk_bf16_f32 v80, v66, v67
	v_cvt_pk_bf16_f32 v81, v68, v69
	global_store_dwordx4 v160, v[78:81], s[98:99] nt
	v_fmamk_f32 v228, v166, 0x3a000000, v155
	v_add_u32_e32 v156, 0x80, v146
	s_nop 0
	v_mad_u32_u24 v157, v156, s52, v134
	v_rsq_f32_e32 v228, v228
	s_nop 0
	s_nop 0
	v_pk_mul_f32 v[62:63], v[62:63], v[228:229] op_sel_hi:[1,0]
	v_pk_mul_f32 v[64:65], v[64:65], v[228:229] op_sel_hi:[1,0]
	v_pk_mul_f32 v[58:59], v[58:59], v[228:229] op_sel_hi:[1,0]
	v_pk_mul_f32 v[60:61], v[60:61], v[228:229] op_sel_hi:[1,0]
	v_pk_mul_f32 v[54:55], v[54:55], v[228:229] op_sel_hi:[1,0]
	v_pk_mul_f32 v[56:57], v[56:57], v[228:229] op_sel_hi:[1,0]
	v_pk_mul_f32 v[50:51], v[50:51], v[228:229] op_sel_hi:[1,0]
	v_pk_mul_f32 v[52:53], v[52:53], v[228:229] op_sel_hi:[1,0]
	v_pk_mul_f32 v[220:221], v[62:63], s[36:37]
	v_pk_mul_f32 v[222:223], v[64:65], s[36:37]
	v_pk_mul_f32 v[224:225], v[58:59], s[36:37]
	v_pk_mul_f32 v[226:227], v[60:61], s[36:37]
	v_exp_f32_e32 v220, v220
	v_exp_f32_e32 v221, v221
	v_exp_f32_e32 v222, v222
	v_exp_f32_e32 v223, v223
	v_exp_f32_e32 v224, v224
	v_exp_f32_e32 v225, v225
	v_exp_f32_e32 v226, v226
	v_exp_f32_e32 v227, v227
	v_pk_add_f32 v[220:221], v[220:221], s[38:39]
	v_pk_add_f32 v[222:223], v[222:223], s[38:39]
	v_pk_add_f32 v[224:225], v[224:225], s[38:39]
	v_pk_add_f32 v[226:227], v[226:227], s[38:39]
	v_rcp_f32_e32 v220, v220
	v_rcp_f32_e32 v221, v221
	v_rcp_f32_e32 v222, v222
	v_rcp_f32_e32 v223, v223
	v_rcp_f32_e32 v224, v224
	v_rcp_f32_e32 v225, v225
	v_rcp_f32_e32 v226, v226
	v_rcp_f32_e32 v227, v227
	v_pk_mul_f32 v[62:63], v[62:63], v[220:221]
	v_pk_mul_f32 v[64:65], v[64:65], v[222:223]
	v_pk_mul_f32 v[58:59], v[58:59], v[224:225]
	v_pk_mul_f32 v[60:61], v[60:61], v[226:227]
	v_pk_mul_f32 v[54:55], v[54:55], v[62:63]
	v_pk_mul_f32 v[56:57], v[56:57], v[64:65]
	v_pk_mul_f32 v[50:51], v[50:51], v[58:59]
	v_pk_mul_f32 v[52:53], v[52:53], v[60:61]
	v_cvt_pk_bf16_f32 v62, v54, v55
	v_cvt_pk_bf16_f32 v63, v56, v57
	v_cvt_pk_bf16_f32 v64, v50, v51
	v_cvt_pk_bf16_f32 v65, v52, v53
	global_store_dwordx4 v157, v[62:65], s[98:99] nt
	v_fmamk_f32 v228, v149, 0x3a000000, v155
	v_add_u32_e32 v156, 0x90, v146
	s_nop 0
	v_mad_u32_u24 v160, v156, s52, v134
	v_rsq_f32_e32 v228, v228
	s_nop 0
	s_nop 0
	v_pk_mul_f32 v[46:47], v[46:47], v[228:229] op_sel_hi:[1,0]
	v_pk_mul_f32 v[48:49], v[48:49], v[228:229] op_sel_hi:[1,0]
	v_pk_mul_f32 v[42:43], v[42:43], v[228:229] op_sel_hi:[1,0]
	v_pk_mul_f32 v[44:45], v[44:45], v[228:229] op_sel_hi:[1,0]
; __device__ __forceinline__ float fast_sigmoid(float x) { return __builtin_amdgcn_rcpf(1.0f + __builtin_amdgcn_exp2f(-1.4426950408889634f * x)); }
; __device__ __forceinline__ u32x4 pack8(const f32x4 a, const f32x4 b) { u32x4 w; w.x = cvt_pk_bf16(a[0], a[1]); w.y = cvt_pk_bf16(a[2], a[3]); w.z = cvt_pk_bf16(b[0], b[1]); w.w = cvt_pk_bf16(b[2], b[3]); return w; }
; #define PG8_BAR __builtin_amdgcn_s_barrier()
; template <class Sched, class Epi>
; __device__ __forceinline__ void gemm_run(LAS unsigned char* lds, const Sched& S, const Epi& E) {
;     ...
;         if (wr == 0) PG8_BAR;
;         if constexpr (!Epi::AFTER_DRAIN) E(acc, cur, wr, wc, fr, fq);
;         if (!has_next) break;
;     __device__ __forceinline__ void operator()(f32x4 (&acc)[2][2][4][2], const Unit& u, int wr, int wc, int fr, int fq) const {
;     ...
;                 for (int m = 0; m < 4; ++m) { const int row = ROWOF(ai, m); const float rs = rsqrtf(rsv[ai * 4 + m] * (1.0f / 2048.0f) + EPS);
;                     f32x4 g0 = acc[ai][0][m][0] * rs, g1 = acc[ai][0][m][1] * rs; const f32x4 u0 = acc[ai][1][m][0] * rs, u1 = acc[ai][1][m][1] * rs;
; #pragma unroll
;                     for (int j = 0; j < 4; ++j) { g0[j] = g0[j] * fast_sigmoid(g0[j]) * u0[j]; g1[j] = g1[j] * fast_sigmoid(g1[j]) * u1[j]; }
;                     *(u32x4*)(P.f_() + (size_t)row * DFF + u.pn * 128 + c8) = pack8(g0, g1); }
	v_pk_mul_f32 v[38:39], v[38:39], v[228:229] op_sel_hi:[1,0]
	v_pk_mul_f32 v[40:41], v[40:41], v[228:229] op_sel_hi:[1,0]
	v_pk_mul_f32 v[34:35], v[34:35], v[228:229] op_sel_hi:[1,0]
	v_pk_mul_f32 v[36:37], v[36:37], v[228:229] op_sel_hi:[1,0]
	v_pk_mul_f32 v[220:221], v[46:47], s[36:37]
	v_pk_mul_f32 v[222:223], v[48:49], s[36:37]
	v_pk_mul_f32 v[224:225], v[42:43], s[36:37]
	v_pk_mul_f32 v[226:227], v[44:45], s[36:37]
	v_exp_f32_e32 v220, v220
	v_exp_f32_e32 v221, v221
	v_exp_f32_e32 v222, v222
	v_exp_f32_e32 v223, v223
	v_exp_f32_e32 v224, v224
	v_exp_f32_e32 v225, v225
	v_exp_f32_e32 v226, v226
	v_exp_f32_e32 v227, v227
	v_pk_add_f32 v[220:221], v[220:221], s[38:39]
	v_pk_add_f32 v[222:223], v[222:223], s[38:39]
	v_pk_add_f32 v[224:225], v[224:225], s[38:39]
	v_pk_add_f32 v[226:227], v[226:227], s[38:39]
	v_rcp_f32_e32 v220, v220
	v_rcp_f32_e32 v221, v221
	v_rcp_f32_e32 v222, v222
	v_rcp_f32_e32 v223, v223
	v_rcp_f32_e32 v224, v224
	v_rcp_f32_e32 v225, v225
	v_rcp_f32_e32 v226, v226
	v_rcp_f32_e32 v227, v227
	v_pk_mul_f32 v[46:47], v[46:47], v[220:221]
	v_pk_mul_f32 v[48:49], v[48:49], v[222:223]
	v_pk_mul_f32 v[42:43], v[42:43], v[224:225]
	v_pk_mul_f32 v[44:45], v[44:45], v[226:227]
	v_pk_mul_f32 v[38:39], v[38:39], v[46:47]
	v_pk_mul_f32 v[40:41], v[40:41], v[48:49]
	v_pk_mul_f32 v[34:35], v[34:35], v[42:43]
	v_pk_mul_f32 v[36:37], v[36:37], v[44:45]
	v_cvt_pk_bf16_f32 v46, v38, v39
	v_cvt_pk_bf16_f32 v47, v40, v41
	v_cvt_pk_bf16_f32 v48, v34, v35
	v_cvt_pk_bf16_f32 v49, v36, v37
	global_store_dwordx4 v160, v[46:49], s[98:99] nt
	v_fmamk_f32 v228, v148, 0x3a000000, v155
	v_add_u32_e32 v156, 0xa0, v146
	s_nop 0
	v_mad_u32_u24 v157, v156, s52, v134
	v_rsq_f32_e32 v228, v228
	s_nop 0
	s_nop 0
	v_pk_mul_f32 v[30:31], v[30:31], v[228:229] op_sel_hi:[1,0]
	v_pk_mul_f32 v[32:33], v[32:33], v[228:229] op_sel_hi:[1,0]
	v_pk_mul_f32 v[26:27], v[26:27], v[228:229] op_sel_hi:[1,0]
	v_pk_mul_f32 v[28:29], v[28:29], v[228:229] op_sel_hi:[1,0]
	v_pk_mul_f32 v[22:23], v[22:23], v[228:229] op_sel_hi:[1,0]
	v_pk_mul_f32 v[24:25], v[24:25], v[228:229] op_sel_hi:[1,0]
	v_pk_mul_f32 v[18:19], v[18:19], v[228:229] op_sel_hi:[1,0]
	v_pk_mul_f32 v[20:21], v[20:21], v[228:229] op_sel_hi:[1,0]
	v_pk_mul_f32 v[220:221], v[30:31], s[36:37]
	v_pk_mul_f32 v[222:223], v[32:33], s[36:37]
	v_pk_mul_f32 v[224:225], v[26:27], s[36:37]
	v_pk_mul_f32 v[226:227], v[28:29], s[36:37]
	v_exp_f32_e32 v220, v220
	v_exp_f32_e32 v221, v221
	v_exp_f32_e32 v222, v222
	v_exp_f32_e32 v223, v223
	v_exp_f32_e32 v224, v224
	v_exp_f32_e32 v225, v225
	v_exp_f32_e32 v226, v226
	v_exp_f32_e32 v227, v227
	v_pk_add_f32 v[220:221], v[220:221], s[38:39]
	v_pk_add_f32 v[222:223], v[222:223], s[38:39]
	v_pk_add_f32 v[224:225], v[224:225], s[38:39]
	v_pk_add_f32 v[226:227], v[226:227], s[38:39]
	v_rcp_f32_e32 v220, v220
	v_rcp_f32_e32 v221, v221
	v_rcp_f32_e32 v222, v222
	v_rcp_f32_e32 v223, v223
	v_rcp_f32_e32 v224, v224
	v_rcp_f32_e32 v225, v225
	v_rcp_f32_e32 v226, v226
	v_rcp_f32_e32 v227, v227
	v_pk_mul_f32 v[30:31], v[30:31], v[220:221]
	v_pk_mul_f32 v[32:33], v[32:33], v[222:223]
	v_pk_mul_f32 v[26:27], v[26:27], v[224:225]
	v_pk_mul_f32 v[28:29], v[28:29], v[226:227]
	v_pk_mul_f32 v[22:23], v[22:23], v[30:31]
	v_pk_mul_f32 v[24:25], v[24:25], v[32:33]
	v_pk_mul_f32 v[18:19], v[18:19], v[26:27]
	v_pk_mul_f32 v[20:21], v[20:21], v[28:29]
	v_cvt_pk_bf16_f32 v30, v22, v23
	v_cvt_pk_bf16_f32 v31, v24, v25
	v_cvt_pk_bf16_f32 v32, v18, v19
	v_cvt_pk_bf16_f32 v33, v20, v21
	global_store_dwordx4 v157, v[30:33], s[98:99] nt
	v_fmamk_f32 v228, v147, 0x3a000000, v155
	v_add_u32_e32 v156, 0xb0, v146
	s_nop 0
	v_mad_u32_u24 v160, v156, s52, v134
	v_rsq_f32_e32 v228, v228
	s_nop 0
	s_nop 0
	v_pk_mul_f32 v[14:15], v[14:15], v[228:229] op_sel_hi:[1,0]
	v_pk_mul_f32 v[16:17], v[16:17], v[228:229] op_sel_hi:[1,0]
	v_pk_mul_f32 v[10:11], v[10:11], v[228:229] op_sel_hi:[1,0]
	v_pk_mul_f32 v[12:13], v[12:13], v[228:229] op_sel_hi:[1,0]
	v_pk_mul_f32 v[6:7], v[6:7], v[228:229] op_sel_hi:[1,0]
	v_pk_mul_f32 v[8:9], v[8:9], v[228:229] op_sel_hi:[1,0]
	v_pk_mul_f32 v[2:3], v[2:3], v[228:229] op_sel_hi:[1,0]
	v_pk_mul_f32 v[4:5], v[4:5], v[228:229] op_sel_hi:[1,0]
	v_pk_mul_f32 v[220:221], v[14:15], s[36:37]
	v_pk_mul_f32 v[222:223], v[16:17], s[36:37]
	v_pk_mul_f32 v[224:225], v[10:11], s[36:37]
	v_pk_mul_f32 v[226:227], v[12:13], s[36:37]
	v_exp_f32_e32 v220, v220
	v_exp_f32_e32 v221, v221
	v_exp_f32_e32 v222, v222
	v_exp_f32_e32 v223, v223
	v_exp_f32_e32 v224, v224
	v_exp_f32_e32 v225, v225
	v_exp_f32_e32 v226, v226
	v_exp_f32_e32 v227, v227
	v_pk_add_f32 v[220:221], v[220:221], s[38:39]
	v_pk_add_f32 v[222:223], v[222:223], s[38:39]
	v_pk_add_f32 v[224:225], v[224:225], s[38:39]
	v_pk_add_f32 v[226:227], v[226:227], s[38:39]
	v_rcp_f32_e32 v220, v220
	v_rcp_f32_e32 v221, v221
	v_rcp_f32_e32 v222, v222
	v_rcp_f32_e32 v223, v223
	v_rcp_f32_e32 v224, v224
	v_rcp_f32_e32 v225, v225
	v_rcp_f32_e32 v226, v226
	v_rcp_f32_e32 v227, v227
	v_pk_mul_f32 v[14:15], v[14:15], v[220:221]
	v_pk_mul_f32 v[16:17], v[16:17], v[222:223]
	v_pk_mul_f32 v[10:11], v[10:11], v[224:225]
	v_pk_mul_f32 v[12:13], v[12:13], v[226:227]
	v_pk_mul_f32 v[6:7], v[6:7], v[14:15]
	v_pk_mul_f32 v[8:9], v[8:9], v[16:17]
	v_pk_mul_f32 v[2:3], v[2:3], v[10:11]
	v_pk_mul_f32 v[4:5], v[4:5], v[12:13]
	v_cvt_pk_bf16_f32 v14, v6, v7
	v_cvt_pk_bf16_f32 v15, v8, v9
	v_cvt_pk_bf16_f32 v16, v2, v3
	v_cvt_pk_bf16_f32 v17, v4, v5
	s_andn2_b64 vcc, exec, s[18:19]
	s_mov_b64 s[18:19], -1
	global_store_dwordx4 v160, v[14:17], s[98:99] nt
	s_cbranch_vccnz .LBB0_995
	s_andn2_b64 vcc, exec, s[4:5]
	s_cbranch_vccnz .LBB0_994
	s_barrier
	s_branch .LBB0_994

; #define PG8_STAGE(bufoff, gbase, RR, ld) do { _Pragma("unroll") for (int _i = 0; _i < 2; ++_i) \
;         __builtin_amdgcn_global_load_lds((const unsigned*)((const char*)(gbase) + (RR)[_i] * (ld) + C2[_i]), (LAS unsigned*)(lds + (bufoff) + ldsw + _i * 8192), 16, 0, 0); } while (0)
; #define PG8_LDA(dst, b, h) do { _Pragma("unroll") for (int m = 0; m < 4; ++m) _Pragma("unroll") for (int k = 0; k < 2; ++k) dst[m][k] = *(const LAS bf16x8*)(lds + PG8_SA(b, h) + aoff + m * 2048 + k * 1024); } while (0)
; #define PG8_LDB(dst, b, h) do { _Pragma("unroll") for (int n = 0; n < 2; ++n) _Pragma("unroll") for (int k = 0; k < 2; ++k) dst[n][k] = *(const LAS bf16x8*)(lds + PG8_SB(b, h) + boff + n * 2048 + k * 1024); } while (0)
; #define PG8_MMA(ai, bj, At, Bt) do { __builtin_amdgcn_s_setprio(1); _Pragma("unroll") for (int m = 0; m < 4; ++m) _Pragma("unroll") for (int n = 0; n < 2; ++n) _Pragma("unroll") for (int k = 0; k < 2; ++k) \
;         acc[ai][bj][m][n] = __builtin_amdgcn_mfma_f32_16x16x32_bf16(Bt[n][k], At[m][k], acc[ai][bj][m][n], 0, 0, 0); __builtin_amdgcn_s_setprio(0); } while (0)
; #define PG8_WAIT_V(n) asm volatile("s_waitcnt vmcnt(" #n ")" ::: "memory")
; #define PG8_WAIT_L(n) asm volatile("s_waitcnt lgkmcnt(" #n ")" ::: "memory")
; template <class Sched, class Epi>
; __device__ __forceinline__ void gemm_run(LAS unsigned char* lds, const Sched& S, const Epi& E) {
;     ...
;         for (int t = 0; t < nt; t += 2) {
;             const bool last = (t == nt - 2);
;             const char* a1 = cA + (size_t)(t + 1) * kstep;
;             const char* a2 = last ? nA : cA + (size_t)(t + 2) * kstep; const char* b2 = last ? nB : cB + (size_t)(t + 2) * kstep;
;             const unsigned la2 = last ? nlda : lda, lb2 = last ? nldb : ldb;
;             const char* a3 = a2 + kstep; const char* b3 = b2 + kstep;
;             PG8_LDB(B0, 0, 0); PG8_LDB(B1, 0, 1); PG8_SCHED; PG8_LDA(At, 0, 0); PG8_STAGE(PG8_SA(1, 1), a1 + (size_t)HALF * lda, RA, lda);
;             PG8_WAIT_V(8); PG8_WAIT_L(0); PG8_BAR; PG8_MMA(0, 0, At, B0); PG8_MMA(0, 1, At, B1); PG8_BAR; PG8_SCHED;
;             PG8_LDA(At, 0, 1); PG8_STAGE(PG8_SB(0, 0), b2, RB, lb2); PG8_STAGE(PG8_SB(0, 1), b2 + (size_t)HALF * lb2, RB, lb2); PG8_STAGE(PG8_SA(0, 0), a2, RA, la2);
;             PG8_WAIT_V(8); PG8_WAIT_L(0); PG8_BAR; PG8_MMA(1, 0, At, B0); PG8_MMA(1, 1, At, B1); PG8_BAR; PG8_SCHED;
.LBB0_1067:
	v_add_u32_e32 v222, 0x10000, v149
	s_add_u32 s65, s28, 0x100
	s_addc_u32 s66, s29, 0
	s_mov_b32 s67, -2
	s_mov_b64 s[28:29], 0
	.p2align 6
.LBB0_1068:
	ds_read_b128 v[152:155], v222
	ds_read_b128 v[156:159], v222 offset:1024
	ds_read_b128 v[160:163], v222 offset:2048
	ds_read_b128 v[164:167], v222 offset:3072
	s_add_u32 s30, s20, s28
	ds_read_b128 v[168:171], v222 offset:16384
	ds_read_b128 v[172:175], v222 offset:17408
	ds_read_b128 v[176:179], v222 offset:18432
	ds_read_b128 v[180:183], v222 offset:19456
	s_addc_u32 s31, s21, s29
	s_mov_b32 s98, s30
	s_mov_b32 s99, s31
	s_add_u32 s30, s30, 0x100
	s_addc_u32 s31, s31, 0
	s_add_u32 s68, s65, s28
	s_addc_u32 s69, s66, s29
	s_cmpk_eq_i32 s28, 0x2b00
	s_cselect_b32 s37, s17, s31
	s_cselect_b32 s36, s16, s30
	s_cselect_b32 s31, s19, s69
	s_cselect_b32 s30, s18, s68
	s_mov_b64 s[100:101], s[36:37]
	s_mov_b32 m0, s52
	ds_read_b128 v[190:193], v150
	ds_read_b128 v[194:197], v150 offset:1024
	ds_read_b128 v[198:201], v150 offset:2048
	ds_read_b128 v[202:205], v150 offset:3072
	ds_read_b128 v[206:209], v150 offset:4096
	ds_read_b128 v[210:213], v150 offset:5120
	ds_read_b128 v[214:217], v150 offset:6144
	ds_read_b128 v[218:221], v150 offset:7168
	global_load_lds_dwordx4 v140, s[98:99]
	s_mov_b32 m0, s53
	s_nop 0
	global_load_lds_dwordx4 v142, s[98:99]
	s_waitcnt vmcnt(8)
	s_waitcnt lgkmcnt(0)
	s_barrier
	s_waitcnt lgkmcnt(0)
	v_mfma_f32_16x16x32_bf16 v[126:129], v[152:155], v[190:193], v[126:129]
	v_mfma_f32_16x16x32_bf16 v[122:125], v[160:163], v[190:193], v[122:125]
	v_mfma_f32_16x16x32_bf16 v[110:113], v[152:155], v[198:201], v[110:113]
	v_mfma_f32_16x16x32_bf16 v[106:109], v[160:163], v[198:201], v[106:109]
	v_mfma_f32_16x16x32_bf16 v[94:97], v[152:155], v[206:209], v[94:97]
	v_mfma_f32_16x16x32_bf16 v[90:93], v[160:163], v[206:209], v[90:93]
	v_mfma_f32_16x16x32_bf16 v[78:81], v[152:155], v[214:217], v[78:81]
	v_mfma_f32_16x16x32_bf16 v[74:77], v[160:163], v[214:217], v[74:77]
	v_mfma_f32_16x16x32_bf16 v[126:129], v[156:159], v[194:197], v[126:129]
	v_mfma_f32_16x16x32_bf16 v[122:125], v[164:167], v[194:197], v[122:125]
	v_mfma_f32_16x16x32_bf16 v[110:113], v[156:159], v[202:205], v[110:113]
	v_mfma_f32_16x16x32_bf16 v[106:109], v[164:167], v[202:205], v[106:109]
	v_mfma_f32_16x16x32_bf16 v[94:97], v[156:159], v[210:213], v[94:97]
	v_mfma_f32_16x16x32_bf16 v[90:93], v[164:167], v[210:213], v[90:93]
	v_mfma_f32_16x16x32_bf16 v[78:81], v[156:159], v[218:221], v[78:81]
	v_mfma_f32_16x16x32_bf16 v[74:77], v[164:167], v[218:221], v[74:77]
	v_mfma_f32_16x16x32_bf16 v[118:121], v[168:171], v[190:193], v[118:121]
	v_mfma_f32_16x16x32_bf16 v[114:117], v[176:179], v[190:193], v[114:117]
	v_mfma_f32_16x16x32_bf16 v[102:105], v[168:171], v[198:201], v[102:105]
	v_mfma_f32_16x16x32_bf16 v[98:101], v[176:179], v[198:201], v[98:101]
	v_mfma_f32_16x16x32_bf16 v[86:89], v[168:171], v[206:209], v[86:89]
	v_mfma_f32_16x16x32_bf16 v[82:85], v[176:179], v[206:209], v[82:85]
	v_mfma_f32_16x16x32_bf16 v[70:73], v[168:171], v[214:217], v[70:73]
	v_mfma_f32_16x16x32_bf16 v[66:69], v[176:179], v[214:217], v[66:69]
	v_mfma_f32_16x16x32_bf16 v[118:121], v[172:175], v[194:197], v[118:121]
	v_mfma_f32_16x16x32_bf16 v[114:117], v[180:183], v[194:197], v[114:117]
	v_mfma_f32_16x16x32_bf16 v[102:105], v[172:175], v[202:205], v[102:105]
	v_mfma_f32_16x16x32_bf16 v[98:101], v[180:183], v[202:205], v[98:101]
	v_mfma_f32_16x16x32_bf16 v[86:89], v[172:175], v[210:213], v[86:89]
	v_mfma_f32_16x16x32_bf16 v[82:85], v[180:183], v[210:213], v[82:85]
	v_mfma_f32_16x16x32_bf16 v[70:73], v[172:175], v[218:221], v[70:73]
	v_mfma_f32_16x16x32_bf16 v[66:69], v[180:183], v[218:221], v[66:69]
	s_barrier
	s_add_u32 s68, s30, 0x160000
	s_mov_b32 m0, s54
	s_addc_u32 s69, s31, 0
	ds_read_b128 v[190:193], v150 offset:16384
	ds_read_b128 v[194:197], v150 offset:17408
	ds_read_b128 v[198:201], v150 offset:18432
	ds_read_b128 v[202:205], v150 offset:19456
	ds_read_b128 v[206:209], v150 offset:20480
	ds_read_b128 v[210:213], v150 offset:21504
	ds_read_b128 v[214:217], v150 offset:22528
	ds_read_b128 v[218:221], v150 offset:23552
	global_load_lds_dwordx4 v132, s[30:31]
	s_mov_b32 m0, s55
	s_nop 0
	global_load_lds_dwordx4 v134, s[30:31]
	s_mov_b32 m0, s56
	s_nop 0
	global_load_lds_dwordx4 v132, s[68:69]
	s_mov_b32 m0, s57
	s_nop 0
	global_load_lds_dwordx4 v134, s[68:69]
	s_mov_b32 m0, s42
	s_nop 0
	global_load_lds_dwordx4 v136, s[36:37]
	s_mov_b32 m0, s43
	s_nop 0
	global_load_lds_dwordx4 v138, s[36:37]
	s_waitcnt vmcnt(8)
	s_waitcnt lgkmcnt(0)
	s_barrier
; #define PG8_STAGE(bufoff, gbase, RR, ld) do { _Pragma("unroll") for (int _i = 0; _i < 2; ++_i) \
;         __builtin_amdgcn_global_load_lds((const unsigned*)((const char*)(gbase) + (RR)[_i] * (ld) + C2[_i]), (LAS unsigned*)(lds + (bufoff) + ldsw + _i * 8192), 16, 0, 0); } while (0)
; #define PG8_LDA(dst, b, h) do { _Pragma("unroll") for (int m = 0; m < 4; ++m) _Pragma("unroll") for (int k = 0; k < 2; ++k) dst[m][k] = *(const LAS bf16x8*)(lds + PG8_SA(b, h) + aoff + m * 2048 + k * 1024); } while (0)
; #define PG8_LDB(dst, b, h) do { _Pragma("unroll") for (int n = 0; n < 2; ++n) _Pragma("unroll") for (int k = 0; k < 2; ++k) dst[n][k] = *(const LAS bf16x8*)(lds + PG8_SB(b, h) + boff + n * 2048 + k * 1024); } while (0)
; #define PG8_MMA(ai, bj, At, Bt) do { __builtin_amdgcn_s_setprio(1); _Pragma("unroll") for (int m = 0; m < 4; ++m) _Pragma("unroll") for (int n = 0; n < 2; ++n) _Pragma("unroll") for (int k = 0; k < 2; ++k) \
;         acc[ai][bj][m][n] = __builtin_amdgcn_mfma_f32_16x16x32_bf16(Bt[n][k], At[m][k], acc[ai][bj][m][n], 0, 0, 0); __builtin_amdgcn_s_setprio(0); } while (0)
; #define PG8_WAIT_V(n) asm volatile("s_waitcnt vmcnt(" #n ")" ::: "memory")
; #define PG8_WAIT_L(n) asm volatile("s_waitcnt lgkmcnt(" #n ")" ::: "memory")
; #define PG8_BAR __builtin_amdgcn_s_barrier()
; #define PG8_SCHED __builtin_amdgcn_sched_barrier(0)
; template <class Sched, class Epi>
; __device__ __forceinline__ void gemm_run(LAS unsigned char* lds, const Sched& S, const Epi& E) {
;     ...
;             PG8_LDA(At, 0, 1); PG8_STAGE(PG8_SB(0, 0), b2, RB, lb2); PG8_STAGE(PG8_SB(0, 1), b2 + (size_t)HALF * lb2, RB, lb2); PG8_STAGE(PG8_SA(0, 0), a2, RA, la2);
;             PG8_WAIT_V(8); PG8_WAIT_L(0); PG8_BAR; PG8_MMA(1, 0, At, B0); PG8_MMA(1, 1, At, B1); PG8_BAR; PG8_SCHED;
;             PG8_LDB(B0, 1, 0); PG8_LDB(B1, 1, 1); PG8_SCHED; PG8_LDA(At, 1, 0); PG8_STAGE(PG8_SA(0, 1), a2 + (size_t)HALF * la2, RA, la2);
;             PG8_WAIT_V(8); PG8_WAIT_L(0); PG8_BAR; PG8_MMA(0, 0, At, B0); PG8_MMA(0, 1, At, B1); PG8_BAR; PG8_SCHED;
	s_waitcnt lgkmcnt(0)
	v_mfma_f32_16x16x32_bf16 v[62:65], v[152:155], v[190:193], v[62:65]
	v_mfma_f32_16x16x32_bf16 v[58:61], v[160:163], v[190:193], v[58:61]
	v_mfma_f32_16x16x32_bf16 v[46:49], v[152:155], v[198:201], v[46:49]
	v_mfma_f32_16x16x32_bf16 v[42:45], v[160:163], v[198:201], v[42:45]
	v_mfma_f32_16x16x32_bf16 v[30:33], v[152:155], v[206:209], v[30:33]
	v_mfma_f32_16x16x32_bf16 v[26:29], v[160:163], v[206:209], v[26:29]
	v_mfma_f32_16x16x32_bf16 v[14:17], v[152:155], v[214:217], v[14:17]
	v_mfma_f32_16x16x32_bf16 v[10:13], v[160:163], v[214:217], v[10:13]
	v_mfma_f32_16x16x32_bf16 v[62:65], v[156:159], v[194:197], v[62:65]
	v_mfma_f32_16x16x32_bf16 v[58:61], v[164:167], v[194:197], v[58:61]
	v_mfma_f32_16x16x32_bf16 v[46:49], v[156:159], v[202:205], v[46:49]
	v_mfma_f32_16x16x32_bf16 v[42:45], v[164:167], v[202:205], v[42:45]
	v_mfma_f32_16x16x32_bf16 v[30:33], v[156:159], v[210:213], v[30:33]
	v_mfma_f32_16x16x32_bf16 v[26:29], v[164:167], v[210:213], v[26:29]
	v_mfma_f32_16x16x32_bf16 v[14:17], v[156:159], v[218:221], v[14:17]
	v_mfma_f32_16x16x32_bf16 v[10:13], v[164:167], v[218:221], v[10:13]
	v_mfma_f32_16x16x32_bf16 v[54:57], v[168:171], v[190:193], v[54:57]
	v_mfma_f32_16x16x32_bf16 v[50:53], v[176:179], v[190:193], v[50:53]
	v_mfma_f32_16x16x32_bf16 v[38:41], v[168:171], v[198:201], v[38:41]
	v_mfma_f32_16x16x32_bf16 v[34:37], v[176:179], v[198:201], v[34:37]
	v_mfma_f32_16x16x32_bf16 v[22:25], v[168:171], v[206:209], v[22:25]
	v_mfma_f32_16x16x32_bf16 v[18:21], v[176:179], v[206:209], v[18:21]
	v_mfma_f32_16x16x32_bf16 v[6:9], v[168:171], v[214:217], v[6:9]
	v_mfma_f32_16x16x32_bf16 v[2:5], v[176:179], v[214:217], v[2:5]
	v_mfma_f32_16x16x32_bf16 v[54:57], v[172:175], v[194:197], v[54:57]
	v_mfma_f32_16x16x32_bf16 v[50:53], v[180:183], v[194:197], v[50:53]
	v_mfma_f32_16x16x32_bf16 v[38:41], v[172:175], v[202:205], v[38:41]
	v_mfma_f32_16x16x32_bf16 v[34:37], v[180:183], v[202:205], v[34:37]
	v_mfma_f32_16x16x32_bf16 v[22:25], v[172:175], v[210:213], v[22:25]
	v_mfma_f32_16x16x32_bf16 v[18:21], v[180:183], v[210:213], v[18:21]
	v_mfma_f32_16x16x32_bf16 v[6:9], v[172:175], v[218:221], v[6:9]
	v_mfma_f32_16x16x32_bf16 v[2:5], v[180:183], v[218:221], v[2:5]
	s_barrier
	ds_read_b128 v[152:155], v222 offset:32768
	ds_read_b128 v[156:159], v222 offset:33792
	ds_read_b128 v[160:163], v222 offset:34816
	ds_read_b128 v[164:167], v222 offset:35840
	ds_read_b128 v[168:171], v222 offset:49152
	ds_read_b128 v[172:175], v222 offset:50176
	ds_read_b128 v[176:179], v222 offset:51200
	ds_read_b128 v[180:183], v222 offset:52224
	s_add_u32 s36, s36, 0x160000
	s_addc_u32 s37, s37, 0
	s_mov_b32 m0, s44
	ds_read_b128 v[190:193], v150 offset:32768
	ds_read_b128 v[194:197], v150 offset:33792
	ds_read_b128 v[198:201], v150 offset:34816
	ds_read_b128 v[202:205], v150 offset:35840
	ds_read_b128 v[206:209], v150 offset:36864
	ds_read_b128 v[210:213], v150 offset:37888
	ds_read_b128 v[214:217], v150 offset:38912
	ds_read_b128 v[218:221], v150 offset:39936
	global_load_lds_dwordx4 v136, s[36:37]
	s_mov_b32 m0, s45
	s_nop 0
	global_load_lds_dwordx4 v138, s[36:37]
	s_waitcnt vmcnt(8)
	s_waitcnt lgkmcnt(0)
	s_barrier
	s_waitcnt lgkmcnt(0)
	v_mfma_f32_16x16x32_bf16 v[126:129], v[152:155], v[190:193], v[126:129]
	v_mfma_f32_16x16x32_bf16 v[122:125], v[160:163], v[190:193], v[122:125]
	v_mfma_f32_16x16x32_bf16 v[110:113], v[152:155], v[198:201], v[110:113]
	v_mfma_f32_16x16x32_bf16 v[106:109], v[160:163], v[198:201], v[106:109]
	v_mfma_f32_16x16x32_bf16 v[94:97], v[152:155], v[206:209], v[94:97]
	v_mfma_f32_16x16x32_bf16 v[90:93], v[160:163], v[206:209], v[90:93]
	v_mfma_f32_16x16x32_bf16 v[78:81], v[152:155], v[214:217], v[78:81]
	v_mfma_f32_16x16x32_bf16 v[74:77], v[160:163], v[214:217], v[74:77]
	v_mfma_f32_16x16x32_bf16 v[126:129], v[156:159], v[194:197], v[126:129]
	v_mfma_f32_16x16x32_bf16 v[122:125], v[164:167], v[194:197], v[122:125]
	v_mfma_f32_16x16x32_bf16 v[110:113], v[156:159], v[202:205], v[110:113]
	v_mfma_f32_16x16x32_bf16 v[106:109], v[164:167], v[202:205], v[106:109]
	v_mfma_f32_16x16x32_bf16 v[94:97], v[156:159], v[210:213], v[94:97]
	v_mfma_f32_16x16x32_bf16 v[90:93], v[164:167], v[210:213], v[90:93]
	v_mfma_f32_16x16x32_bf16 v[78:81], v[156:159], v[218:221], v[78:81]
	v_mfma_f32_16x16x32_bf16 v[74:77], v[164:167], v[218:221], v[74:77]
	v_mfma_f32_16x16x32_bf16 v[118:121], v[168:171], v[190:193], v[118:121]
	v_mfma_f32_16x16x32_bf16 v[114:117], v[176:179], v[190:193], v[114:117]
	v_mfma_f32_16x16x32_bf16 v[102:105], v[168:171], v[198:201], v[102:105]
	v_mfma_f32_16x16x32_bf16 v[98:101], v[176:179], v[198:201], v[98:101]
	v_mfma_f32_16x16x32_bf16 v[86:89], v[168:171], v[206:209], v[86:89]
	v_mfma_f32_16x16x32_bf16 v[82:85], v[176:179], v[206:209], v[82:85]
	v_mfma_f32_16x16x32_bf16 v[70:73], v[168:171], v[214:217], v[70:73]
	v_mfma_f32_16x16x32_bf16 v[66:69], v[176:179], v[214:217], v[66:69]
	v_mfma_f32_16x16x32_bf16 v[118:121], v[172:175], v[194:197], v[118:121]
	v_mfma_f32_16x16x32_bf16 v[114:117], v[180:183], v[194:197], v[114:117]
	v_mfma_f32_16x16x32_bf16 v[102:105], v[172:175], v[202:205], v[102:105]
	v_mfma_f32_16x16x32_bf16 v[98:101], v[180:183], v[202:205], v[98:101]
	v_mfma_f32_16x16x32_bf16 v[86:89], v[172:175], v[210:213], v[86:89]
	v_mfma_f32_16x16x32_bf16 v[82:85], v[180:183], v[210:213], v[82:85]
	v_mfma_f32_16x16x32_bf16 v[70:73], v[172:175], v[218:221], v[70:73]
	v_mfma_f32_16x16x32_bf16 v[66:69], v[180:183], v[218:221], v[66:69]
	s_barrier
; #define PG8_STAGE(bufoff, gbase, RR, ld) do { _Pragma("unroll") for (int _i = 0; _i < 2; ++_i) \
;         __builtin_amdgcn_global_load_lds((const unsigned*)((const char*)(gbase) + (RR)[_i] * (ld) + C2[_i]), (LAS unsigned*)(lds + (bufoff) + ldsw + _i * 8192), 16, 0, 0); } while (0)
; #define PG8_LDA(dst, b, h) do { _Pragma("unroll") for (int m = 0; m < 4; ++m) _Pragma("unroll") for (int k = 0; k < 2; ++k) dst[m][k] = *(const LAS bf16x8*)(lds + PG8_SA(b, h) + aoff + m * 2048 + k * 1024); } while (0)
; #define PG8_MMA(ai, bj, At, Bt) do { __builtin_amdgcn_s_setprio(1); _Pragma("unroll") for (int m = 0; m < 4; ++m) _Pragma("unroll") for (int n = 0; n < 2; ++n) _Pragma("unroll") for (int k = 0; k < 2; ++k) \
;         acc[ai][bj][m][n] = __builtin_amdgcn_mfma_f32_16x16x32_bf16(Bt[n][k], At[m][k], acc[ai][bj][m][n], 0, 0, 0); __builtin_amdgcn_s_setprio(0); } while (0)
; #define PG8_WAIT_V(n) asm volatile("s_waitcnt vmcnt(" #n ")" ::: "memory")
; #define PG8_WAIT_L(n) asm volatile("s_waitcnt lgkmcnt(" #n ")" ::: "memory")
; #define PG8_BAR __builtin_amdgcn_s_barrier()
; #define PG8_SCHED __builtin_amdgcn_sched_barrier(0)
; template <class Sched, class Epi>
; __device__ __forceinline__ void gemm_run(LAS unsigned char* lds, const Sched& S, const Epi& E) {
;     ...
;             PG8_LDA(At, 1, 1); PG8_STAGE(PG8_SB(1, 0), b3, RB, lb2); PG8_STAGE(PG8_SB(1, 1), b3 + (size_t)HALF * lb2, RB, lb2); PG8_STAGE(PG8_SA(1, 0), a3, RA, la2);
;             PG8_WAIT_V(8); PG8_WAIT_L(0); PG8_BAR; PG8_MMA(1, 0, At, B0); PG8_MMA(1, 1, At, B1); PG8_BAR; PG8_SCHED;
;         }
	s_mov_b32 m0, s60
	ds_read_b128 v[190:193], v150 offset:49152
	ds_read_b128 v[194:197], v150 offset:50176
	ds_read_b128 v[198:201], v150 offset:51200
	ds_read_b128 v[202:205], v150 offset:52224
	ds_read_b128 v[206:209], v150 offset:53248
	ds_read_b128 v[210:213], v150 offset:54272
	ds_read_b128 v[214:217], v150 offset:55296
	ds_read_b128 v[218:221], v150 offset:56320
	s_add_u32 s98, s30, 0x80
	s_addc_u32 s99, s31, 0
	global_load_lds_dwordx4 v132, s[98:99]
	s_add_i32 m0, s60, 0x2000
	s_nop 0
	global_load_lds_dwordx4 v134, s[98:99]
	s_add_u32 s30, s30, 0x160080
	s_addc_u32 s31, s31, 0
	s_add_i32 s36, s59, s35
	s_mov_b32 m0, s36
	s_nop 0
	global_load_lds_dwordx4 v132, s[30:31]
	s_add_i32 m0, s36, 0x2000
	s_nop 0
	global_load_lds_dwordx4 v134, s[30:31]
	s_mov_b32 m0, s47
	s_nop 0
	s_add_u32 s100, s100, 0x80
	s_addc_u32 s101, s101, 0
	global_load_lds_dwordx4 v136, s[100:101]
	s_mov_b32 m0, s48
	s_nop 0
	global_load_lds_dwordx4 v138, s[100:101]
	s_waitcnt vmcnt(8)
	s_waitcnt lgkmcnt(0)
	s_barrier
	s_waitcnt lgkmcnt(0)
	v_mfma_f32_16x16x32_bf16 v[62:65], v[152:155], v[190:193], v[62:65]
	v_mfma_f32_16x16x32_bf16 v[58:61], v[160:163], v[190:193], v[58:61]
	v_mfma_f32_16x16x32_bf16 v[46:49], v[152:155], v[198:201], v[46:49]
	v_mfma_f32_16x16x32_bf16 v[42:45], v[160:163], v[198:201], v[42:45]
	v_mfma_f32_16x16x32_bf16 v[30:33], v[152:155], v[206:209], v[30:33]
	v_mfma_f32_16x16x32_bf16 v[26:29], v[160:163], v[206:209], v[26:29]
	v_mfma_f32_16x16x32_bf16 v[14:17], v[152:155], v[214:217], v[14:17]
	v_mfma_f32_16x16x32_bf16 v[10:13], v[160:163], v[214:217], v[10:13]
	v_mfma_f32_16x16x32_bf16 v[62:65], v[156:159], v[194:197], v[62:65]
	v_mfma_f32_16x16x32_bf16 v[58:61], v[164:167], v[194:197], v[58:61]
	v_mfma_f32_16x16x32_bf16 v[46:49], v[156:159], v[202:205], v[46:49]
	v_mfma_f32_16x16x32_bf16 v[42:45], v[164:167], v[202:205], v[42:45]
	v_mfma_f32_16x16x32_bf16 v[30:33], v[156:159], v[210:213], v[30:33]
	v_mfma_f32_16x16x32_bf16 v[26:29], v[164:167], v[210:213], v[26:29]
	v_mfma_f32_16x16x32_bf16 v[14:17], v[156:159], v[218:221], v[14:17]
	v_mfma_f32_16x16x32_bf16 v[10:13], v[164:167], v[218:221], v[10:13]
	v_mfma_f32_16x16x32_bf16 v[54:57], v[168:171], v[190:193], v[54:57]
	v_mfma_f32_16x16x32_bf16 v[50:53], v[176:179], v[190:193], v[50:53]
	v_mfma_f32_16x16x32_bf16 v[38:41], v[168:171], v[198:201], v[38:41]
	v_mfma_f32_16x16x32_bf16 v[34:37], v[176:179], v[198:201], v[34:37]
	v_mfma_f32_16x16x32_bf16 v[22:25], v[168:171], v[206:209], v[22:25]
	v_mfma_f32_16x16x32_bf16 v[18:21], v[176:179], v[206:209], v[18:21]
	v_mfma_f32_16x16x32_bf16 v[6:9], v[168:171], v[214:217], v[6:9]
	v_mfma_f32_16x16x32_bf16 v[2:5], v[176:179], v[214:217], v[2:5]
	v_mfma_f32_16x16x32_bf16 v[54:57], v[172:175], v[194:197], v[54:57]
	v_mfma_f32_16x16x32_bf16 v[50:53], v[180:183], v[194:197], v[50:53]
	v_mfma_f32_16x16x32_bf16 v[38:41], v[172:175], v[202:205], v[38:41]
	v_mfma_f32_16x16x32_bf16 v[34:37], v[180:183], v[202:205], v[34:37]
	v_mfma_f32_16x16x32_bf16 v[22:25], v[172:175], v[210:213], v[22:25]
	v_mfma_f32_16x16x32_bf16 v[18:21], v[180:183], v[210:213], v[18:21]
	v_mfma_f32_16x16x32_bf16 v[6:9], v[172:175], v[218:221], v[6:9]
	v_mfma_f32_16x16x32_bf16 v[2:5], v[180:183], v[218:221], v[2:5]
	s_barrier
	s_add_i32 s67, s67, 2
	s_add_u32 s28, s28, 0x100
	s_addc_u32 s29, s29, 0
	s_cmpk_gt_u32 s67, 0x55
	s_cbranch_scc0 .LBB0_1068
	s_and_b64 vcc, exec, s[12:13]
	s_cbranch_vccz .LBB0_1071
	s_barrier
